# FFN-up epilogues: pairs of 8-byte hidden stores merged into 16-byte stores via permlane16_swap (16 -> 8 store instructions per wave per tile)
# speedup vs baseline: 1.0255x; 1.0015x over previous
.LBB0_237:
	v_bfe_u32 v246, v197, 4, 1
	v_mul_u32_u24_e32 v246, 0x15ff8, v246
	v_mov_b32_e32 v247, 0
	v_lshl_add_u32 v140, s41, 8, v145
	v_ashrrev_i32_e32 v141, 31, v140
	v_lshlrev_b64 v[164:165], 6, v[140:141]
	v_lshl_add_u64 v[164:165], s[66:67], 0, v[164:165]
	v_and_b32_e32 v166, 48, v197
	v_mov_b32_e32 v167, 0
	v_lshl_add_u64 v[164:165], v[164:165], 0, v[166:167]
	s_mov_b64 s[20:21], 0x2000
	v_lshl_add_u64 v[166:167], v[164:165], 0, s[20:21]
	global_load_dwordx4 v[204:207], v[164:165], off
	global_load_dwordx4 v[208:211], v[164:165], off offset:1024
	global_load_dwordx4 v[212:215], v[164:165], off offset:2048
	global_load_dwordx4 v[216:219], v[164:165], off offset:3072
	global_load_dwordx4 v[220:223], v[166:167], off
	global_load_dwordx4 v[224:227], v[166:167], off offset:1024
	global_load_dwordx4 v[228:231], v[166:167], off offset:2048
	global_load_dwordx4 v[232:235], v[166:167], off offset:3072
	v_lshl_or_b32 v142, s40, 7, v162
	v_ashrrev_i32_e32 v143, 31, v142
	s_waitcnt vmcnt(0)
	v_add_f32_e32 v204, v204, v205
	v_add_f32_e32 v206, v206, v207
	v_add_f32_e32 v204, v204, v206
	v_mov_b32_e32 v205, v204
	s_nop 1
	v_permlane16_swap_b32_e32 v204, v205
	v_add_f32_e32 v204, v204, v205
	v_mov_b32_e32 v205, v204
	s_nop 1
	v_permlane32_swap_b32_e32 v204, v205
	v_add_f32_e32 v141, v204, v205
	v_fmamk_f32 v141, v141, 0x3a800000, v161
	v_cmp_gt_f32_e32 vcc, s62, v141
	v_mul_f32_e32 v144, 0x4b800000, v141
	s_nop 0
	v_cndmask_b32_e32 v141, v141, v144, vcc
	v_rsq_f32_e32 v141, v141
	s_nop 0
	v_mul_f32_e32 v144, 0x45800000, v141
	v_cndmask_b32_e32 v144, v141, v144, vcc
	v_pk_mul_f32 v[126:127], v[126:127], v[144:145] op_sel_hi:[1,0]
	v_pk_mul_f32 v[122:123], v[122:123], v[144:145] op_sel_hi:[1,0]
	v_mul_f32_e32 v141, 0xbfb8aa3b, v126
	v_exp_f32_e32 v141, v141
	v_pk_mul_f32 v[124:125], v[124:125], v[144:145] op_sel_hi:[1,0]
	v_pk_mul_f32 v[118:119], v[118:119], v[144:145] op_sel_hi:[1,0]
	v_pk_mul_f32 v[114:115], v[114:115], v[144:145] op_sel_hi:[1,0]
	v_add_f32_e32 v141, 1.0, v141
	v_rcp_f32_e32 v164, v141
	v_mul_f32_e32 v141, 0xbfb8aa3b, v127
	v_exp_f32_e32 v141, v141
	v_pk_mul_f32 v[116:117], v[116:117], v[144:145] op_sel_hi:[1,0]
	v_add_f32_e32 v141, 1.0, v141
	v_rcp_f32_e32 v165, v141
	s_nop 0
	v_pk_mul_f32 v[126:127], v[126:127], v[164:165]
	s_nop 0
	v_pk_mul_f32 v[122:123], v[122:123], v[126:127]
	v_pk_mul_f32 v[126:127], v[128:129], v[144:145] op_sel_hi:[1,0]
	s_nop 0
	v_mul_f32_e32 v128, 0xbfb8aa3b, v126
	v_mul_f32_e32 v129, 0xbfb8aa3b, v127
	v_exp_f32_e32 v128, v128
	v_exp_f32_e32 v129, v129
	v_add_f32_e32 v128, 1.0, v128
	v_add_f32_e32 v129, 1.0, v129
	v_rcp_f32_e32 v128, v128
	v_rcp_f32_e32 v129, v129
	s_nop 0
	v_pk_mul_f32 v[126:127], v[126:127], v[128:129]
	s_nop 0
	v_pk_mul_f32 v[124:125], v[124:125], v[126:127]
	v_cvt_pk_bf16_f32 v126, v122, v123
	v_mov_b64_e32 v[122:123], s[8:9]
	v_cvt_pk_bf16_f32 v127, v124, v125
	v_mad_i64_i32 v[128:129], s[20:21], v140, s1, v[122:123]
	v_lshlrev_b64 v[124:125], 1, v[142:143]
	v_lshl_add_u64 v[128:129], v[128:129], 0, v[124:125]
	v_lshl_add_u64 v[244:245], v[128:129], 0, v[246:247]
	v_mov_b32_e32 v236, v126
	v_mov_b32_e32 v237, v127
	v_mul_f32_e32 v126, 0xbfb8aa3b, v118
	v_mul_f32_e32 v127, 0xbfb8aa3b, v119
	v_exp_f32_e32 v126, v126
	v_exp_f32_e32 v127, v127
	v_add_f32_e32 v126, 1.0, v126
	v_add_f32_e32 v127, 1.0, v127
	v_rcp_f32_e32 v126, v126
	v_rcp_f32_e32 v127, v127
	s_nop 0
	v_pk_mul_f32 v[118:119], v[118:119], v[126:127]
	s_nop 0
	v_pk_mul_f32 v[114:115], v[114:115], v[118:119]
	v_pk_mul_f32 v[118:119], v[120:121], v[144:145] op_sel_hi:[1,0]
	v_or_b32_e32 v126, 16, v140
	v_mul_f32_e32 v120, 0xbfb8aa3b, v118
	v_mul_f32_e32 v121, 0xbfb8aa3b, v119
	v_exp_f32_e32 v120, v120
	v_exp_f32_e32 v121, v121
	v_cvt_pk_bf16_f32 v114, v114, v115
	v_ashrrev_i32_e32 v127, 31, v126
	v_add_f32_e32 v120, 1.0, v120
	v_add_f32_e32 v121, 1.0, v121
	v_rcp_f32_e32 v120, v120
	v_rcp_f32_e32 v121, v121
	s_nop 0
	v_pk_mul_f32 v[118:119], v[118:119], v[120:121]
	s_nop 0
	v_pk_mul_f32 v[116:117], v[116:117], v[118:119]
	s_nop 0
	v_cvt_pk_bf16_f32 v115, v116, v117
	v_mov_b32_e32 v240, v114
	v_mov_b32_e32 v241, v115
	v_add_f32_e32 v208, v208, v209
	v_add_f32_e32 v210, v210, v211
	v_add_f32_e32 v208, v208, v210
	v_mov_b32_e32 v209, v208
	s_nop 1
	v_permlane16_swap_b32_e32 v208, v209
	v_add_f32_e32 v208, v208, v209
	v_mov_b32_e32 v209, v208
	s_nop 1
	v_permlane32_swap_b32_e32 v208, v209
	v_add_f32_e32 v114, v208, v209
	v_fmamk_f32 v114, v114, 0x3a800000, v161
	v_cmp_gt_f32_e32 vcc, s62, v114
	v_mul_f32_e32 v115, 0x4b800000, v114
	s_nop 0
	v_cndmask_b32_e32 v114, v114, v115, vcc
	v_rsq_f32_e32 v114, v114
	s_nop 0
	v_mul_f32_e32 v115, 0x45800000, v114
	v_cndmask_b32_e32 v114, v114, v115, vcc
	v_pk_mul_f32 v[110:111], v[110:111], v[114:115] op_sel_hi:[1,0]
	s_nop 0
	v_mul_f32_e32 v115, 0xbfb8aa3b, v110
	v_exp_f32_e32 v115, v115
	s_nop 0
	v_add_f32_e32 v115, 1.0, v115
	v_rcp_f32_e32 v116, v115
	v_mul_f32_e32 v115, 0xbfb8aa3b, v111
	v_exp_f32_e32 v115, v115
	s_nop 0
	v_add_f32_e32 v115, 1.0, v115
	v_rcp_f32_e32 v117, v115
	v_pk_mul_f32 v[106:107], v[106:107], v[114:115] op_sel_hi:[1,0]
	v_pk_mul_f32 v[108:109], v[108:109], v[114:115] op_sel_hi:[1,0]
	v_pk_mul_f32 v[102:103], v[102:103], v[114:115] op_sel_hi:[1,0]
	v_pk_mul_f32 v[110:111], v[110:111], v[116:117]
	v_pk_mul_f32 v[98:99], v[98:99], v[114:115] op_sel_hi:[1,0]
	v_pk_mul_f32 v[106:107], v[106:107], v[110:111]
	v_pk_mul_f32 v[110:111], v[112:113], v[114:115] op_sel_hi:[1,0]
	v_cvt_pk_bf16_f32 v106, v106, v107
	v_mul_f32_e32 v112, 0xbfb8aa3b, v110
	v_mul_f32_e32 v113, 0xbfb8aa3b, v111
	v_exp_f32_e32 v112, v112
	v_exp_f32_e32 v113, v113
	v_pk_mul_f32 v[100:101], v[100:101], v[114:115] op_sel_hi:[1,0]
	v_add_f32_e32 v112, 1.0, v112
	v_add_f32_e32 v113, 1.0, v113
	v_rcp_f32_e32 v112, v112
	v_rcp_f32_e32 v113, v113
	s_nop 0
	v_pk_mul_f32 v[110:111], v[110:111], v[112:113]
	s_nop 0
	v_pk_mul_f32 v[108:109], v[108:109], v[110:111]
	s_nop 0
	v_cvt_pk_bf16_f32 v107, v108, v109
	v_mad_i64_i32 v[108:109], s[20:21], v126, s1, v[122:123]
	v_lshl_add_u64 v[108:109], v[108:109], 0, v[124:125]
	v_mov_b32_e32 v238, v106
	v_mov_b32_e32 v239, v107
	s_nop 1
	v_permlane16_swap_b32_e32 v236, v238
	v_permlane16_swap_b32_e32 v237, v239
	global_store_dwordx4 v[244:245], v[236:239], off
	v_mul_f32_e32 v106, 0xbfb8aa3b, v102
	v_mul_f32_e32 v107, 0xbfb8aa3b, v103
	v_exp_f32_e32 v106, v106
	v_exp_f32_e32 v107, v107
	v_add_f32_e32 v106, 1.0, v106
	v_add_f32_e32 v107, 1.0, v107
	v_rcp_f32_e32 v106, v106
	v_rcp_f32_e32 v107, v107
	s_nop 0
	v_pk_mul_f32 v[102:103], v[102:103], v[106:107]
	s_nop 0
	v_pk_mul_f32 v[98:99], v[98:99], v[102:103]
	v_pk_mul_f32 v[102:103], v[104:105], v[114:115] op_sel_hi:[1,0]
	v_or_b32_e32 v106, 32, v140
	v_mul_f32_e32 v104, 0xbfb8aa3b, v102
	v_mul_f32_e32 v105, 0xbfb8aa3b, v103
	v_exp_f32_e32 v104, v104
	v_exp_f32_e32 v105, v105
	v_cvt_pk_bf16_f32 v98, v98, v99
	v_ashrrev_i32_e32 v107, 31, v106
	v_add_f32_e32 v104, 1.0, v104
	v_add_f32_e32 v105, 1.0, v105
	v_rcp_f32_e32 v104, v104
	v_rcp_f32_e32 v105, v105
	s_nop 0
	v_pk_mul_f32 v[102:103], v[102:103], v[104:105]
	s_nop 0
	v_pk_mul_f32 v[100:101], v[100:101], v[102:103]
	s_nop 0
	v_cvt_pk_bf16_f32 v99, v100, v101
	v_mov_b32_e32 v242, v98
	v_mov_b32_e32 v243, v99
	s_nop 1
	v_permlane16_swap_b32_e32 v240, v242
	v_permlane16_swap_b32_e32 v241, v243
	global_store_dwordx4 v[244:245], v[240:243], off offset:128
	v_add_f32_e32 v212, v212, v213
	v_add_f32_e32 v214, v214, v215
	v_add_f32_e32 v212, v212, v214
	v_mov_b32_e32 v213, v212
	s_nop 1
	v_permlane16_swap_b32_e32 v212, v213
	v_add_f32_e32 v212, v212, v213
	v_mov_b32_e32 v213, v212
	s_nop 1
	v_permlane32_swap_b32_e32 v212, v213
	v_add_f32_e32 v98, v212, v213
	v_fmamk_f32 v98, v98, 0x3a800000, v161
	v_cmp_gt_f32_e32 vcc, s62, v98
	v_mul_f32_e32 v99, 0x4b800000, v98
	s_nop 0
	v_cndmask_b32_e32 v98, v98, v99, vcc
	v_rsq_f32_e32 v98, v98
	s_nop 0
	v_mul_f32_e32 v99, 0x45800000, v98
	v_cndmask_b32_e32 v98, v98, v99, vcc
	v_pk_mul_f32 v[94:95], v[94:95], v[98:99] op_sel_hi:[1,0]
	s_nop 0
	v_mul_f32_e32 v99, 0xbfb8aa3b, v94
	v_exp_f32_e32 v99, v99
	s_nop 0
	v_add_f32_e32 v99, 1.0, v99
	v_rcp_f32_e32 v100, v99
	v_mul_f32_e32 v99, 0xbfb8aa3b, v95
	v_exp_f32_e32 v99, v99
	s_nop 0
	v_add_f32_e32 v99, 1.0, v99
	v_rcp_f32_e32 v101, v99
	v_pk_mul_f32 v[90:91], v[90:91], v[98:99] op_sel_hi:[1,0]
	v_pk_mul_f32 v[92:93], v[92:93], v[98:99] op_sel_hi:[1,0]
	v_pk_mul_f32 v[86:87], v[86:87], v[98:99] op_sel_hi:[1,0]
	v_pk_mul_f32 v[94:95], v[94:95], v[100:101]
	v_pk_mul_f32 v[82:83], v[82:83], v[98:99] op_sel_hi:[1,0]
	v_pk_mul_f32 v[90:91], v[90:91], v[94:95]
	v_pk_mul_f32 v[94:95], v[96:97], v[98:99] op_sel_hi:[1,0]
	v_cvt_pk_bf16_f32 v90, v90, v91
	v_mul_f32_e32 v96, 0xbfb8aa3b, v94
	v_mul_f32_e32 v97, 0xbfb8aa3b, v95
	v_exp_f32_e32 v96, v96
	v_exp_f32_e32 v97, v97
	v_pk_mul_f32 v[84:85], v[84:85], v[98:99] op_sel_hi:[1,0]
	v_add_f32_e32 v96, 1.0, v96
	v_add_f32_e32 v97, 1.0, v97
	v_rcp_f32_e32 v96, v96
	v_rcp_f32_e32 v97, v97
	s_nop 0
	v_pk_mul_f32 v[94:95], v[94:95], v[96:97]
	s_nop 0
	v_pk_mul_f32 v[92:93], v[92:93], v[94:95]
	s_nop 0
	v_cvt_pk_bf16_f32 v91, v92, v93
	v_mad_i64_i32 v[92:93], s[20:21], v106, s1, v[122:123]
	v_lshl_add_u64 v[92:93], v[92:93], 0, v[124:125]
	v_lshl_add_u64 v[244:245], v[92:93], 0, v[246:247]
	v_mov_b32_e32 v236, v90
	v_mov_b32_e32 v237, v91
	v_mul_f32_e32 v90, 0xbfb8aa3b, v86
	v_mul_f32_e32 v91, 0xbfb8aa3b, v87
	v_exp_f32_e32 v90, v90
	v_exp_f32_e32 v91, v91
	v_add_f32_e32 v90, 1.0, v90
	v_add_f32_e32 v91, 1.0, v91
	v_rcp_f32_e32 v90, v90
	v_rcp_f32_e32 v91, v91
	s_nop 0
	v_pk_mul_f32 v[86:87], v[86:87], v[90:91]
	s_nop 0
	v_pk_mul_f32 v[82:83], v[82:83], v[86:87]
	v_pk_mul_f32 v[86:87], v[88:89], v[98:99] op_sel_hi:[1,0]
	v_or_b32_e32 v90, 48, v140
	v_mul_f32_e32 v88, 0xbfb8aa3b, v86
	v_mul_f32_e32 v89, 0xbfb8aa3b, v87
	v_exp_f32_e32 v88, v88
	v_exp_f32_e32 v89, v89
	v_cvt_pk_bf16_f32 v82, v82, v83
	v_ashrrev_i32_e32 v91, 31, v90
	v_add_f32_e32 v88, 1.0, v88
	v_add_f32_e32 v89, 1.0, v89
	v_rcp_f32_e32 v88, v88
	v_rcp_f32_e32 v89, v89
	s_nop 0
	v_pk_mul_f32 v[86:87], v[86:87], v[88:89]
	s_nop 0
	v_pk_mul_f32 v[84:85], v[84:85], v[86:87]
	s_nop 0
	v_cvt_pk_bf16_f32 v83, v84, v85
	v_mov_b32_e32 v240, v82
	v_mov_b32_e32 v241, v83
	v_add_f32_e32 v216, v216, v217
	v_add_f32_e32 v218, v218, v219
	v_add_f32_e32 v216, v216, v218
	v_mov_b32_e32 v217, v216
	s_nop 1
	v_permlane16_swap_b32_e32 v216, v217
	v_add_f32_e32 v216, v216, v217
	v_mov_b32_e32 v217, v216
	s_nop 1
	v_permlane32_swap_b32_e32 v216, v217
	v_add_f32_e32 v82, v216, v217
	v_fmamk_f32 v82, v82, 0x3a800000, v161
	v_cmp_gt_f32_e32 vcc, s62, v82
	v_mul_f32_e32 v83, 0x4b800000, v82
	s_nop 0
	v_cndmask_b32_e32 v82, v82, v83, vcc
	v_rsq_f32_e32 v82, v82
	s_nop 0
	v_mul_f32_e32 v83, 0x45800000, v82
	v_cndmask_b32_e32 v82, v82, v83, vcc
	v_pk_mul_f32 v[78:79], v[78:79], v[82:83] op_sel_hi:[1,0]
	s_nop 0
	v_mul_f32_e32 v83, 0xbfb8aa3b, v78
	v_exp_f32_e32 v83, v83
	s_nop 0
	v_add_f32_e32 v83, 1.0, v83
	v_rcp_f32_e32 v84, v83
	v_mul_f32_e32 v83, 0xbfb8aa3b, v79
	v_exp_f32_e32 v83, v83
	s_nop 0
	v_add_f32_e32 v83, 1.0, v83
	v_rcp_f32_e32 v85, v83
	v_pk_mul_f32 v[74:75], v[74:75], v[82:83] op_sel_hi:[1,0]
	v_pk_mul_f32 v[76:77], v[76:77], v[82:83] op_sel_hi:[1,0]
	v_pk_mul_f32 v[70:71], v[70:71], v[82:83] op_sel_hi:[1,0]
	v_pk_mul_f32 v[78:79], v[78:79], v[84:85]
	v_pk_mul_f32 v[66:67], v[66:67], v[82:83] op_sel_hi:[1,0]
	v_pk_mul_f32 v[74:75], v[74:75], v[78:79]
	v_pk_mul_f32 v[78:79], v[80:81], v[82:83] op_sel_hi:[1,0]
	v_cvt_pk_bf16_f32 v74, v74, v75
	v_mul_f32_e32 v80, 0xbfb8aa3b, v78
	v_mul_f32_e32 v81, 0xbfb8aa3b, v79
	v_exp_f32_e32 v80, v80
	v_exp_f32_e32 v81, v81
	v_pk_mul_f32 v[68:69], v[68:69], v[82:83] op_sel_hi:[1,0]
	v_add_f32_e32 v80, 1.0, v80
	v_add_f32_e32 v81, 1.0, v81
	v_rcp_f32_e32 v80, v80
	v_rcp_f32_e32 v81, v81
	s_nop 0
	v_pk_mul_f32 v[78:79], v[78:79], v[80:81]
	s_nop 0
	v_pk_mul_f32 v[76:77], v[76:77], v[78:79]
	s_nop 0
	v_cvt_pk_bf16_f32 v75, v76, v77
	v_mad_i64_i32 v[76:77], s[20:21], v90, s1, v[122:123]
	v_lshl_add_u64 v[76:77], v[76:77], 0, v[124:125]
	v_mov_b32_e32 v238, v74
	v_mov_b32_e32 v239, v75
	s_nop 1
	v_permlane16_swap_b32_e32 v236, v238
	v_permlane16_swap_b32_e32 v237, v239
	global_store_dwordx4 v[244:245], v[236:239], off
	v_mul_f32_e32 v74, 0xbfb8aa3b, v70
	v_mul_f32_e32 v75, 0xbfb8aa3b, v71
	v_exp_f32_e32 v74, v74
	v_exp_f32_e32 v75, v75
	v_add_f32_e32 v74, 1.0, v74
	v_add_f32_e32 v75, 1.0, v75
	v_rcp_f32_e32 v74, v74
	v_rcp_f32_e32 v75, v75
	s_nop 0
	v_pk_mul_f32 v[70:71], v[70:71], v[74:75]
	s_nop 0
	v_pk_mul_f32 v[66:67], v[66:67], v[70:71]
	v_pk_mul_f32 v[70:71], v[72:73], v[82:83] op_sel_hi:[1,0]
	v_add_u32_e32 v74, 0x80, v140
	v_mul_f32_e32 v72, 0xbfb8aa3b, v70
	v_mul_f32_e32 v73, 0xbfb8aa3b, v71
	v_exp_f32_e32 v72, v72
	v_exp_f32_e32 v73, v73
	v_cvt_pk_bf16_f32 v66, v66, v67
	v_ashrrev_i32_e32 v75, 31, v74
	v_add_f32_e32 v72, 1.0, v72
	v_add_f32_e32 v73, 1.0, v73
	v_rcp_f32_e32 v72, v72
	v_rcp_f32_e32 v73, v73
	s_nop 0
	v_pk_mul_f32 v[70:71], v[70:71], v[72:73]
	s_nop 0
	v_pk_mul_f32 v[68:69], v[68:69], v[70:71]
	s_nop 0
	v_cvt_pk_bf16_f32 v67, v68, v69
	v_mov_b32_e32 v242, v66
	v_mov_b32_e32 v243, v67
	s_nop 1
	v_permlane16_swap_b32_e32 v240, v242
	v_permlane16_swap_b32_e32 v241, v243
	global_store_dwordx4 v[244:245], v[240:243], off offset:128
	v_add_f32_e32 v220, v220, v221
	v_add_f32_e32 v222, v222, v223
	v_add_f32_e32 v220, v220, v222
	v_mov_b32_e32 v221, v220
	s_nop 1
	v_permlane16_swap_b32_e32 v220, v221
	v_add_f32_e32 v220, v220, v221
	v_mov_b32_e32 v221, v220
	s_nop 1
	v_permlane32_swap_b32_e32 v220, v221
	v_add_f32_e32 v66, v220, v221
	v_fmamk_f32 v66, v66, 0x3a800000, v161
	v_cmp_gt_f32_e32 vcc, s62, v66
	v_mul_f32_e32 v67, 0x4b800000, v66
	s_nop 0
	v_cndmask_b32_e32 v66, v66, v67, vcc
	v_rsq_f32_e32 v66, v66
	s_nop 0
	v_mul_f32_e32 v67, 0x45800000, v66
	v_cndmask_b32_e32 v66, v66, v67, vcc
	v_pk_mul_f32 v[62:63], v[62:63], v[66:67] op_sel_hi:[1,0]
	s_nop 0
	v_mul_f32_e32 v67, 0xbfb8aa3b, v62
	v_exp_f32_e32 v67, v67
	s_nop 0
	v_add_f32_e32 v67, 1.0, v67
	v_rcp_f32_e32 v68, v67
	v_mul_f32_e32 v67, 0xbfb8aa3b, v63
	v_exp_f32_e32 v67, v67
	s_nop 0
	v_add_f32_e32 v67, 1.0, v67
	v_rcp_f32_e32 v69, v67
	v_pk_mul_f32 v[58:59], v[58:59], v[66:67] op_sel_hi:[1,0]
	v_pk_mul_f32 v[60:61], v[60:61], v[66:67] op_sel_hi:[1,0]
	v_pk_mul_f32 v[54:55], v[54:55], v[66:67] op_sel_hi:[1,0]
	v_pk_mul_f32 v[62:63], v[62:63], v[68:69]
	v_pk_mul_f32 v[50:51], v[50:51], v[66:67] op_sel_hi:[1,0]
	v_pk_mul_f32 v[58:59], v[58:59], v[62:63]
	v_pk_mul_f32 v[62:63], v[64:65], v[66:67] op_sel_hi:[1,0]
	v_cvt_pk_bf16_f32 v58, v58, v59
	v_mul_f32_e32 v64, 0xbfb8aa3b, v62
	v_mul_f32_e32 v65, 0xbfb8aa3b, v63
	v_exp_f32_e32 v64, v64
	v_exp_f32_e32 v65, v65
	v_pk_mul_f32 v[52:53], v[52:53], v[66:67] op_sel_hi:[1,0]
	v_add_f32_e32 v64, 1.0, v64
	v_add_f32_e32 v65, 1.0, v65
	v_rcp_f32_e32 v64, v64
	v_rcp_f32_e32 v65, v65
	s_nop 0
	v_pk_mul_f32 v[62:63], v[62:63], v[64:65]
	s_nop 0
	v_pk_mul_f32 v[60:61], v[60:61], v[62:63]
	s_nop 0
	v_cvt_pk_bf16_f32 v59, v60, v61
	v_mad_i64_i32 v[60:61], s[20:21], v74, s1, v[122:123]
	v_lshl_add_u64 v[60:61], v[60:61], 0, v[124:125]
	v_lshl_add_u64 v[244:245], v[60:61], 0, v[246:247]
	v_mov_b32_e32 v236, v58
	v_mov_b32_e32 v237, v59
	v_mul_f32_e32 v58, 0xbfb8aa3b, v54
	v_mul_f32_e32 v59, 0xbfb8aa3b, v55
	v_exp_f32_e32 v58, v58
	v_exp_f32_e32 v59, v59
	v_add_f32_e32 v58, 1.0, v58
	v_add_f32_e32 v59, 1.0, v59
	v_rcp_f32_e32 v58, v58
	v_rcp_f32_e32 v59, v59
	s_nop 0
	v_pk_mul_f32 v[54:55], v[54:55], v[58:59]
	s_nop 0
	v_pk_mul_f32 v[50:51], v[50:51], v[54:55]
	v_pk_mul_f32 v[54:55], v[56:57], v[66:67] op_sel_hi:[1,0]
	v_add_u32_e32 v58, 0x90, v140
	v_mul_f32_e32 v56, 0xbfb8aa3b, v54
	v_mul_f32_e32 v57, 0xbfb8aa3b, v55
	v_exp_f32_e32 v56, v56
	v_exp_f32_e32 v57, v57
	v_cvt_pk_bf16_f32 v50, v50, v51
	v_ashrrev_i32_e32 v59, 31, v58
	v_add_f32_e32 v56, 1.0, v56
	v_add_f32_e32 v57, 1.0, v57
	v_rcp_f32_e32 v56, v56
	v_rcp_f32_e32 v57, v57
	s_nop 0
	v_pk_mul_f32 v[54:55], v[54:55], v[56:57]
	s_nop 0
	v_pk_mul_f32 v[52:53], v[52:53], v[54:55]
	s_nop 0
	v_cvt_pk_bf16_f32 v51, v52, v53
	v_mov_b32_e32 v240, v50
	v_mov_b32_e32 v241, v51
	v_add_f32_e32 v224, v224, v225
	v_add_f32_e32 v226, v226, v227
	v_add_f32_e32 v224, v224, v226
	v_mov_b32_e32 v225, v224
	s_nop 1
	v_permlane16_swap_b32_e32 v224, v225
	v_add_f32_e32 v224, v224, v225
	v_mov_b32_e32 v225, v224
	s_nop 1
	v_permlane32_swap_b32_e32 v224, v225
	v_add_f32_e32 v50, v224, v225
	v_fmamk_f32 v50, v50, 0x3a800000, v161
	v_cmp_gt_f32_e32 vcc, s62, v50
	v_mul_f32_e32 v51, 0x4b800000, v50
	s_nop 0
	v_cndmask_b32_e32 v50, v50, v51, vcc
	v_rsq_f32_e32 v50, v50
	s_nop 0
	v_mul_f32_e32 v51, 0x45800000, v50
	v_cndmask_b32_e32 v50, v50, v51, vcc
	v_pk_mul_f32 v[46:47], v[46:47], v[50:51] op_sel_hi:[1,0]
	s_nop 0
	v_mul_f32_e32 v51, 0xbfb8aa3b, v46
	v_exp_f32_e32 v51, v51
	s_nop 0
	v_add_f32_e32 v51, 1.0, v51
	v_rcp_f32_e32 v52, v51
	v_mul_f32_e32 v51, 0xbfb8aa3b, v47
	v_exp_f32_e32 v51, v51
	s_nop 0
	v_add_f32_e32 v51, 1.0, v51
	v_rcp_f32_e32 v53, v51
	v_pk_mul_f32 v[42:43], v[42:43], v[50:51] op_sel_hi:[1,0]
	v_pk_mul_f32 v[44:45], v[44:45], v[50:51] op_sel_hi:[1,0]
	v_pk_mul_f32 v[38:39], v[38:39], v[50:51] op_sel_hi:[1,0]
	v_pk_mul_f32 v[46:47], v[46:47], v[52:53]
	v_pk_mul_f32 v[34:35], v[34:35], v[50:51] op_sel_hi:[1,0]
	v_pk_mul_f32 v[42:43], v[42:43], v[46:47]
	v_pk_mul_f32 v[46:47], v[48:49], v[50:51] op_sel_hi:[1,0]
	v_cvt_pk_bf16_f32 v42, v42, v43
	v_mul_f32_e32 v48, 0xbfb8aa3b, v46
	v_mul_f32_e32 v49, 0xbfb8aa3b, v47
	v_exp_f32_e32 v48, v48
	v_exp_f32_e32 v49, v49
	v_pk_mul_f32 v[36:37], v[36:37], v[50:51] op_sel_hi:[1,0]
	v_add_f32_e32 v48, 1.0, v48
	v_add_f32_e32 v49, 1.0, v49
	v_rcp_f32_e32 v48, v48
	v_rcp_f32_e32 v49, v49
	s_nop 0
	v_pk_mul_f32 v[46:47], v[46:47], v[48:49]
	s_nop 0
	v_pk_mul_f32 v[44:45], v[44:45], v[46:47]
	s_nop 0
	v_cvt_pk_bf16_f32 v43, v44, v45
	v_mad_i64_i32 v[44:45], s[20:21], v58, s1, v[122:123]
	v_lshl_add_u64 v[44:45], v[44:45], 0, v[124:125]
	v_mov_b32_e32 v238, v42
	v_mov_b32_e32 v239, v43
	s_nop 1
	v_permlane16_swap_b32_e32 v236, v238
	v_permlane16_swap_b32_e32 v237, v239
	global_store_dwordx4 v[244:245], v[236:239], off
	v_mul_f32_e32 v42, 0xbfb8aa3b, v38
	v_mul_f32_e32 v43, 0xbfb8aa3b, v39
	v_exp_f32_e32 v42, v42
	v_exp_f32_e32 v43, v43
	v_add_f32_e32 v42, 1.0, v42
	v_add_f32_e32 v43, 1.0, v43
	v_rcp_f32_e32 v42, v42
	v_rcp_f32_e32 v43, v43
	s_nop 0
	v_pk_mul_f32 v[38:39], v[38:39], v[42:43]
	s_nop 0
	v_pk_mul_f32 v[34:35], v[34:35], v[38:39]
	v_pk_mul_f32 v[38:39], v[40:41], v[50:51] op_sel_hi:[1,0]
	v_add_u32_e32 v42, 0xa0, v140
	v_mul_f32_e32 v40, 0xbfb8aa3b, v38
	v_mul_f32_e32 v41, 0xbfb8aa3b, v39
	v_exp_f32_e32 v40, v40
	v_exp_f32_e32 v41, v41
	v_cvt_pk_bf16_f32 v34, v34, v35
	v_ashrrev_i32_e32 v43, 31, v42
	v_add_f32_e32 v40, 1.0, v40
	v_add_f32_e32 v41, 1.0, v41
	v_rcp_f32_e32 v40, v40
	v_rcp_f32_e32 v41, v41
	s_nop 0
	v_pk_mul_f32 v[38:39], v[38:39], v[40:41]
	s_nop 0
	v_pk_mul_f32 v[36:37], v[36:37], v[38:39]
	s_nop 0
	v_cvt_pk_bf16_f32 v35, v36, v37
	v_mov_b32_e32 v242, v34
	v_mov_b32_e32 v243, v35
	s_nop 1
	v_permlane16_swap_b32_e32 v240, v242
	v_permlane16_swap_b32_e32 v241, v243
	global_store_dwordx4 v[244:245], v[240:243], off offset:128
	v_add_f32_e32 v228, v228, v229
	v_add_f32_e32 v230, v230, v231
	v_add_f32_e32 v228, v228, v230
	v_mov_b32_e32 v229, v228
	s_nop 1
	v_permlane16_swap_b32_e32 v228, v229
	v_add_f32_e32 v228, v228, v229
	v_mov_b32_e32 v229, v228
	s_nop 1
	v_permlane32_swap_b32_e32 v228, v229
	v_add_f32_e32 v34, v228, v229
	v_fmamk_f32 v34, v34, 0x3a800000, v161
	v_cmp_gt_f32_e32 vcc, s62, v34
	v_mul_f32_e32 v35, 0x4b800000, v34
	s_nop 0
	v_cndmask_b32_e32 v34, v34, v35, vcc
	v_rsq_f32_e32 v34, v34
	s_nop 0
	v_mul_f32_e32 v35, 0x45800000, v34
	v_cndmask_b32_e32 v34, v34, v35, vcc
	v_pk_mul_f32 v[30:31], v[30:31], v[34:35] op_sel_hi:[1,0]
	s_nop 0
	v_mul_f32_e32 v35, 0xbfb8aa3b, v30
	v_exp_f32_e32 v35, v35
	s_nop 0
	v_add_f32_e32 v35, 1.0, v35
	v_rcp_f32_e32 v36, v35
	v_mul_f32_e32 v35, 0xbfb8aa3b, v31
	v_exp_f32_e32 v35, v35
	s_nop 0
	v_add_f32_e32 v35, 1.0, v35
	v_rcp_f32_e32 v37, v35
	v_pk_mul_f32 v[26:27], v[26:27], v[34:35] op_sel_hi:[1,0]
	v_pk_mul_f32 v[28:29], v[28:29], v[34:35] op_sel_hi:[1,0]
	v_pk_mul_f32 v[22:23], v[22:23], v[34:35] op_sel_hi:[1,0]
	v_pk_mul_f32 v[30:31], v[30:31], v[36:37]
	v_pk_mul_f32 v[18:19], v[18:19], v[34:35] op_sel_hi:[1,0]
	v_pk_mul_f32 v[26:27], v[26:27], v[30:31]
	v_pk_mul_f32 v[30:31], v[32:33], v[34:35] op_sel_hi:[1,0]
	v_cvt_pk_bf16_f32 v26, v26, v27
	v_mul_f32_e32 v32, 0xbfb8aa3b, v30
	v_mul_f32_e32 v33, 0xbfb8aa3b, v31
	v_exp_f32_e32 v32, v32
	v_exp_f32_e32 v33, v33
	v_pk_mul_f32 v[20:21], v[20:21], v[34:35] op_sel_hi:[1,0]
	v_add_f32_e32 v32, 1.0, v32
	v_add_f32_e32 v33, 1.0, v33
	v_rcp_f32_e32 v32, v32
	v_rcp_f32_e32 v33, v33
	s_nop 0
	v_pk_mul_f32 v[30:31], v[30:31], v[32:33]
	s_nop 0
	v_pk_mul_f32 v[28:29], v[28:29], v[30:31]
	s_nop 0
	v_cvt_pk_bf16_f32 v27, v28, v29
	v_mad_i64_i32 v[28:29], s[20:21], v42, s1, v[122:123]
	v_lshl_add_u64 v[28:29], v[28:29], 0, v[124:125]
	v_lshl_add_u64 v[244:245], v[28:29], 0, v[246:247]
	v_mov_b32_e32 v236, v26
	v_mov_b32_e32 v237, v27
	v_mul_f32_e32 v26, 0xbfb8aa3b, v22
	v_mul_f32_e32 v27, 0xbfb8aa3b, v23
	v_exp_f32_e32 v26, v26
	v_exp_f32_e32 v27, v27
	v_add_f32_e32 v26, 1.0, v26
	v_add_f32_e32 v27, 1.0, v27
	v_rcp_f32_e32 v26, v26
	v_rcp_f32_e32 v27, v27
	s_nop 0
	v_pk_mul_f32 v[22:23], v[22:23], v[26:27]
	s_nop 0
	v_pk_mul_f32 v[18:19], v[18:19], v[22:23]
	v_pk_mul_f32 v[22:23], v[24:25], v[34:35] op_sel_hi:[1,0]
	v_add_u32_e32 v26, 0xb0, v140
	v_mul_f32_e32 v24, 0xbfb8aa3b, v22
	v_mul_f32_e32 v25, 0xbfb8aa3b, v23
	v_exp_f32_e32 v24, v24
	v_exp_f32_e32 v25, v25
	v_cvt_pk_bf16_f32 v18, v18, v19
	v_ashrrev_i32_e32 v27, 31, v26
	v_add_f32_e32 v24, 1.0, v24
	v_add_f32_e32 v25, 1.0, v25
	v_rcp_f32_e32 v24, v24
	v_rcp_f32_e32 v25, v25
	s_nop 0
	v_pk_mul_f32 v[22:23], v[22:23], v[24:25]
	s_nop 0
	v_pk_mul_f32 v[20:21], v[20:21], v[22:23]
	s_nop 0
	v_cvt_pk_bf16_f32 v19, v20, v21
	v_mov_b32_e32 v240, v18
	v_mov_b32_e32 v241, v19
	v_add_f32_e32 v232, v232, v233
	v_add_f32_e32 v234, v234, v235
	v_add_f32_e32 v232, v232, v234
	v_mov_b32_e32 v233, v232
	s_nop 1
	v_permlane16_swap_b32_e32 v232, v233
	v_add_f32_e32 v232, v232, v233
	v_mov_b32_e32 v233, v232
	s_nop 1
	v_permlane32_swap_b32_e32 v232, v233
	v_add_f32_e32 v18, v232, v233
	v_fmamk_f32 v18, v18, 0x3a800000, v161
	v_cmp_gt_f32_e32 vcc, s62, v18
	v_mul_f32_e32 v19, 0x4b800000, v18
	s_nop 0
	v_cndmask_b32_e32 v18, v18, v19, vcc
	v_rsq_f32_e32 v18, v18
	s_nop 0
	v_mul_f32_e32 v19, 0x45800000, v18
	v_cndmask_b32_e32 v18, v18, v19, vcc
	v_pk_mul_f32 v[14:15], v[14:15], v[18:19] op_sel_hi:[1,0]
	s_andn2_b64 vcc, exec, s[4:5]
	v_mul_f32_e32 v19, 0xbfb8aa3b, v14
	v_exp_f32_e32 v19, v19
	s_nop 0
	v_add_f32_e32 v19, 1.0, v19
	v_rcp_f32_e32 v20, v19
	v_mul_f32_e32 v19, 0xbfb8aa3b, v15
	v_exp_f32_e32 v19, v19
	s_nop 0
	v_add_f32_e32 v19, 1.0, v19
	v_rcp_f32_e32 v21, v19
	v_pk_mul_f32 v[10:11], v[10:11], v[18:19] op_sel_hi:[1,0]
	v_pk_mul_f32 v[12:13], v[12:13], v[18:19] op_sel_hi:[1,0]
	v_pk_mul_f32 v[6:7], v[6:7], v[18:19] op_sel_hi:[1,0]
	v_pk_mul_f32 v[14:15], v[14:15], v[20:21]
	v_pk_mul_f32 v[2:3], v[2:3], v[18:19] op_sel_hi:[1,0]
	v_pk_mul_f32 v[10:11], v[10:11], v[14:15]
	v_pk_mul_f32 v[14:15], v[16:17], v[18:19] op_sel_hi:[1,0]
	v_cvt_pk_bf16_f32 v10, v10, v11
	v_mul_f32_e32 v16, 0xbfb8aa3b, v14
	v_mul_f32_e32 v17, 0xbfb8aa3b, v15
	v_exp_f32_e32 v16, v16
	v_exp_f32_e32 v17, v17
	v_pk_mul_f32 v[4:5], v[4:5], v[18:19] op_sel_hi:[1,0]
	v_add_f32_e32 v16, 1.0, v16
	v_add_f32_e32 v17, 1.0, v17
	v_rcp_f32_e32 v16, v16
	v_rcp_f32_e32 v17, v17
	s_nop 0
	v_pk_mul_f32 v[14:15], v[14:15], v[16:17]
	s_nop 0
	v_pk_mul_f32 v[12:13], v[12:13], v[14:15]
	s_nop 0
	v_cvt_pk_bf16_f32 v11, v12, v13
	v_mad_i64_i32 v[12:13], s[20:21], v26, s1, v[122:123]
	v_lshl_add_u64 v[12:13], v[12:13], 0, v[124:125]
	v_mov_b32_e32 v238, v10
	v_mov_b32_e32 v239, v11
	s_nop 1
	v_permlane16_swap_b32_e32 v236, v238
	v_permlane16_swap_b32_e32 v237, v239
	global_store_dwordx4 v[244:245], v[236:239], off
	v_mul_f32_e32 v10, 0xbfb8aa3b, v6
	v_mul_f32_e32 v11, 0xbfb8aa3b, v7
	v_exp_f32_e32 v10, v10
	v_exp_f32_e32 v11, v11
	s_mov_b64 s[20:21], -1
	v_add_f32_e32 v10, 1.0, v10
	v_add_f32_e32 v11, 1.0, v11
	v_rcp_f32_e32 v10, v10
	v_rcp_f32_e32 v11, v11
	s_nop 0
	v_pk_mul_f32 v[6:7], v[6:7], v[10:11]
	s_nop 0
	v_pk_mul_f32 v[2:3], v[2:3], v[6:7]
	v_pk_mul_f32 v[6:7], v[8:9], v[18:19] op_sel_hi:[1,0]
	v_cvt_pk_bf16_f32 v2, v2, v3
	v_mul_f32_e32 v8, 0xbfb8aa3b, v6
	v_mul_f32_e32 v9, 0xbfb8aa3b, v7
	v_exp_f32_e32 v8, v8
	v_exp_f32_e32 v9, v9
	v_add_f32_e32 v8, 1.0, v8
	v_add_f32_e32 v9, 1.0, v9
	v_rcp_f32_e32 v8, v8
	v_rcp_f32_e32 v9, v9
	s_nop 0
	v_pk_mul_f32 v[6:7], v[6:7], v[8:9]
	s_nop 0
	v_pk_mul_f32 v[4:5], v[4:5], v[6:7]
	s_nop 0
	v_cvt_pk_bf16_f32 v3, v4, v5
	v_mov_b32_e32 v242, v2
	v_mov_b32_e32 v243, v3
	s_nop 1
	v_permlane16_swap_b32_e32 v240, v242
	v_permlane16_swap_b32_e32 v241, v243
	global_store_dwordx4 v[244:245], v[240:243], off offset:128
	s_cbranch_vccnz .LBB0_230
	s_andn2_b64 vcc, exec, s[6:7]
	s_cbranch_vccnz .LBB0_229
	s_barrier
	s_branch .LBB0_229

.LBB0_1605:
	v_bfe_u32 v246, v197, 4, 1
	v_mul_u32_u24_e32 v246, 0x15ff8, v246
	v_mov_b32_e32 v247, 0
	v_lshl_add_u32 v140, s41, 8, v145
	v_ashrrev_i32_e32 v141, 31, v140
	v_lshlrev_b64 v[164:165], 6, v[140:141]
	v_lshl_add_u64 v[164:165], s[66:67], 0, v[164:165]
	v_and_b32_e32 v166, 48, v197
	v_mov_b32_e32 v167, 0
	v_lshl_add_u64 v[164:165], v[164:165], 0, v[166:167]
	s_mov_b64 s[20:21], 0x2000
	v_lshl_add_u64 v[166:167], v[164:165], 0, s[20:21]
	global_load_dwordx4 v[204:207], v[164:165], off
	global_load_dwordx4 v[208:211], v[164:165], off offset:1024
	global_load_dwordx4 v[212:215], v[164:165], off offset:2048
	global_load_dwordx4 v[216:219], v[164:165], off offset:3072
	global_load_dwordx4 v[220:223], v[166:167], off
	global_load_dwordx4 v[224:227], v[166:167], off offset:1024
	global_load_dwordx4 v[228:231], v[166:167], off offset:2048
	global_load_dwordx4 v[232:235], v[166:167], off offset:3072
	v_lshl_or_b32 v142, s40, 7, v162
	v_ashrrev_i32_e32 v143, 31, v142
	s_waitcnt vmcnt(0)
	v_add_f32_e32 v204, v204, v205
	v_add_f32_e32 v206, v206, v207
	v_add_f32_e32 v204, v204, v206
	v_mov_b32_e32 v205, v204
	s_nop 1
	v_permlane16_swap_b32_e32 v204, v205
	v_add_f32_e32 v204, v204, v205
	v_mov_b32_e32 v205, v204
	s_nop 1
	v_permlane32_swap_b32_e32 v204, v205
	v_add_f32_e32 v141, v204, v205
	v_fmamk_f32 v141, v141, 0x3a800000, v161
	v_cmp_gt_f32_e32 vcc, s62, v141
	v_mul_f32_e32 v144, 0x4b800000, v141
	s_nop 0
	v_cndmask_b32_e32 v141, v141, v144, vcc
	v_rsq_f32_e32 v141, v141
	s_nop 0
	v_mul_f32_e32 v144, 0x45800000, v141
	v_cndmask_b32_e32 v144, v141, v144, vcc
	v_pk_mul_f32 v[126:127], v[126:127], v[144:145] op_sel_hi:[1,0]
	v_pk_mul_f32 v[122:123], v[122:123], v[144:145] op_sel_hi:[1,0]
	v_mul_f32_e32 v141, 0xbfb8aa3b, v126
	v_exp_f32_e32 v141, v141
	v_pk_mul_f32 v[124:125], v[124:125], v[144:145] op_sel_hi:[1,0]
	v_pk_mul_f32 v[118:119], v[118:119], v[144:145] op_sel_hi:[1,0]
	v_pk_mul_f32 v[114:115], v[114:115], v[144:145] op_sel_hi:[1,0]
	v_add_f32_e32 v141, 1.0, v141
	v_rcp_f32_e32 v164, v141
	v_mul_f32_e32 v141, 0xbfb8aa3b, v127
	v_exp_f32_e32 v141, v141
	v_pk_mul_f32 v[116:117], v[116:117], v[144:145] op_sel_hi:[1,0]
	v_add_f32_e32 v141, 1.0, v141
	v_rcp_f32_e32 v165, v141
	s_nop 0
	v_pk_mul_f32 v[126:127], v[126:127], v[164:165]
	s_nop 0
	v_pk_mul_f32 v[122:123], v[122:123], v[126:127]
	v_pk_mul_f32 v[126:127], v[128:129], v[144:145] op_sel_hi:[1,0]
	s_nop 0
	v_mul_f32_e32 v128, 0xbfb8aa3b, v126
	v_mul_f32_e32 v129, 0xbfb8aa3b, v127
	v_exp_f32_e32 v128, v128
	v_exp_f32_e32 v129, v129
	v_add_f32_e32 v128, 1.0, v128
	v_add_f32_e32 v129, 1.0, v129
	v_rcp_f32_e32 v128, v128
	v_rcp_f32_e32 v129, v129
	s_nop 0
	v_pk_mul_f32 v[126:127], v[126:127], v[128:129]
	s_nop 0
	v_pk_mul_f32 v[124:125], v[124:125], v[126:127]
	v_cvt_pk_bf16_f32 v126, v122, v123
	v_mov_b64_e32 v[122:123], s[8:9]
	v_cvt_pk_bf16_f32 v127, v124, v125
	v_mad_i64_i32 v[128:129], s[20:21], v140, s1, v[122:123]
	v_lshlrev_b64 v[124:125], 1, v[142:143]
	v_lshl_add_u64 v[128:129], v[128:129], 0, v[124:125]
	v_lshl_add_u64 v[244:245], v[128:129], 0, v[246:247]
	v_mov_b32_e32 v236, v126
	v_mov_b32_e32 v237, v127
	v_mul_f32_e32 v126, 0xbfb8aa3b, v118
	v_mul_f32_e32 v127, 0xbfb8aa3b, v119
	v_exp_f32_e32 v126, v126
	v_exp_f32_e32 v127, v127
	v_add_f32_e32 v126, 1.0, v126
	v_add_f32_e32 v127, 1.0, v127
	v_rcp_f32_e32 v126, v126
	v_rcp_f32_e32 v127, v127
	s_nop 0
	v_pk_mul_f32 v[118:119], v[118:119], v[126:127]
	s_nop 0
	v_pk_mul_f32 v[114:115], v[114:115], v[118:119]
	v_pk_mul_f32 v[118:119], v[120:121], v[144:145] op_sel_hi:[1,0]
	v_or_b32_e32 v126, 16, v140
	v_mul_f32_e32 v120, 0xbfb8aa3b, v118
	v_mul_f32_e32 v121, 0xbfb8aa3b, v119
	v_exp_f32_e32 v120, v120
	v_exp_f32_e32 v121, v121
	v_cvt_pk_bf16_f32 v114, v114, v115
	v_ashrrev_i32_e32 v127, 31, v126
	v_add_f32_e32 v120, 1.0, v120
	v_add_f32_e32 v121, 1.0, v121
	v_rcp_f32_e32 v120, v120
	v_rcp_f32_e32 v121, v121
	s_nop 0
	v_pk_mul_f32 v[118:119], v[118:119], v[120:121]
	s_nop 0
	v_pk_mul_f32 v[116:117], v[116:117], v[118:119]
	s_nop 0
	v_cvt_pk_bf16_f32 v115, v116, v117
	v_mov_b32_e32 v240, v114
	v_mov_b32_e32 v241, v115
	v_add_f32_e32 v208, v208, v209
	v_add_f32_e32 v210, v210, v211
	v_add_f32_e32 v208, v208, v210
	v_mov_b32_e32 v209, v208
	s_nop 1
	v_permlane16_swap_b32_e32 v208, v209
	v_add_f32_e32 v208, v208, v209
	v_mov_b32_e32 v209, v208
	s_nop 1
	v_permlane32_swap_b32_e32 v208, v209
	v_add_f32_e32 v114, v208, v209
	v_fmamk_f32 v114, v114, 0x3a800000, v161
	v_cmp_gt_f32_e32 vcc, s62, v114
	v_mul_f32_e32 v115, 0x4b800000, v114
	s_nop 0
	v_cndmask_b32_e32 v114, v114, v115, vcc
	v_rsq_f32_e32 v114, v114
	s_nop 0
	v_mul_f32_e32 v115, 0x45800000, v114
	v_cndmask_b32_e32 v114, v114, v115, vcc
	v_pk_mul_f32 v[110:111], v[110:111], v[114:115] op_sel_hi:[1,0]
	s_nop 0
	v_mul_f32_e32 v115, 0xbfb8aa3b, v110
	v_exp_f32_e32 v115, v115
	s_nop 0
	v_add_f32_e32 v115, 1.0, v115
	v_rcp_f32_e32 v116, v115
	v_mul_f32_e32 v115, 0xbfb8aa3b, v111
	v_exp_f32_e32 v115, v115
	s_nop 0
	v_add_f32_e32 v115, 1.0, v115
	v_rcp_f32_e32 v117, v115
	v_pk_mul_f32 v[106:107], v[106:107], v[114:115] op_sel_hi:[1,0]
	v_pk_mul_f32 v[108:109], v[108:109], v[114:115] op_sel_hi:[1,0]
	v_pk_mul_f32 v[102:103], v[102:103], v[114:115] op_sel_hi:[1,0]
	v_pk_mul_f32 v[110:111], v[110:111], v[116:117]
	v_pk_mul_f32 v[98:99], v[98:99], v[114:115] op_sel_hi:[1,0]
	v_pk_mul_f32 v[106:107], v[106:107], v[110:111]
	v_pk_mul_f32 v[110:111], v[112:113], v[114:115] op_sel_hi:[1,0]
	v_cvt_pk_bf16_f32 v106, v106, v107
	v_mul_f32_e32 v112, 0xbfb8aa3b, v110
	v_mul_f32_e32 v113, 0xbfb8aa3b, v111
	v_exp_f32_e32 v112, v112
	v_exp_f32_e32 v113, v113
	v_pk_mul_f32 v[100:101], v[100:101], v[114:115] op_sel_hi:[1,0]
	v_add_f32_e32 v112, 1.0, v112
	v_add_f32_e32 v113, 1.0, v113
	v_rcp_f32_e32 v112, v112
	v_rcp_f32_e32 v113, v113
	s_nop 0
	v_pk_mul_f32 v[110:111], v[110:111], v[112:113]
	s_nop 0
	v_pk_mul_f32 v[108:109], v[108:109], v[110:111]
	s_nop 0
	v_cvt_pk_bf16_f32 v107, v108, v109
	v_mad_i64_i32 v[108:109], s[20:21], v126, s1, v[122:123]
	v_lshl_add_u64 v[108:109], v[108:109], 0, v[124:125]
	v_mov_b32_e32 v238, v106
	v_mov_b32_e32 v239, v107
	s_nop 1
	v_permlane16_swap_b32_e32 v236, v238
	v_permlane16_swap_b32_e32 v237, v239
	global_store_dwordx4 v[244:245], v[236:239], off
	v_mul_f32_e32 v106, 0xbfb8aa3b, v102
	v_mul_f32_e32 v107, 0xbfb8aa3b, v103
	v_exp_f32_e32 v106, v106
	v_exp_f32_e32 v107, v107
	v_add_f32_e32 v106, 1.0, v106
	v_add_f32_e32 v107, 1.0, v107
	v_rcp_f32_e32 v106, v106
	v_rcp_f32_e32 v107, v107
	s_nop 0
	v_pk_mul_f32 v[102:103], v[102:103], v[106:107]
	s_nop 0
	v_pk_mul_f32 v[98:99], v[98:99], v[102:103]
	v_pk_mul_f32 v[102:103], v[104:105], v[114:115] op_sel_hi:[1,0]
	v_or_b32_e32 v106, 32, v140
	v_mul_f32_e32 v104, 0xbfb8aa3b, v102
	v_mul_f32_e32 v105, 0xbfb8aa3b, v103
	v_exp_f32_e32 v104, v104
	v_exp_f32_e32 v105, v105
	v_cvt_pk_bf16_f32 v98, v98, v99
	v_ashrrev_i32_e32 v107, 31, v106
	v_add_f32_e32 v104, 1.0, v104
	v_add_f32_e32 v105, 1.0, v105
	v_rcp_f32_e32 v104, v104
	v_rcp_f32_e32 v105, v105
	s_nop 0
	v_pk_mul_f32 v[102:103], v[102:103], v[104:105]
	s_nop 0
	v_pk_mul_f32 v[100:101], v[100:101], v[102:103]
	s_nop 0
	v_cvt_pk_bf16_f32 v99, v100, v101
	v_mov_b32_e32 v242, v98
	v_mov_b32_e32 v243, v99
	s_nop 1
	v_permlane16_swap_b32_e32 v240, v242
	v_permlane16_swap_b32_e32 v241, v243
	global_store_dwordx4 v[244:245], v[240:243], off offset:128
	v_add_f32_e32 v212, v212, v213
	v_add_f32_e32 v214, v214, v215
	v_add_f32_e32 v212, v212, v214
	v_mov_b32_e32 v213, v212
	s_nop 1
	v_permlane16_swap_b32_e32 v212, v213
	v_add_f32_e32 v212, v212, v213
	v_mov_b32_e32 v213, v212
	s_nop 1
	v_permlane32_swap_b32_e32 v212, v213
	v_add_f32_e32 v98, v212, v213
	v_fmamk_f32 v98, v98, 0x3a800000, v161
	v_cmp_gt_f32_e32 vcc, s62, v98
	v_mul_f32_e32 v99, 0x4b800000, v98
	s_nop 0
	v_cndmask_b32_e32 v98, v98, v99, vcc
	v_rsq_f32_e32 v98, v98
	s_nop 0
	v_mul_f32_e32 v99, 0x45800000, v98
	v_cndmask_b32_e32 v98, v98, v99, vcc
	v_pk_mul_f32 v[94:95], v[94:95], v[98:99] op_sel_hi:[1,0]
	s_nop 0
	v_mul_f32_e32 v99, 0xbfb8aa3b, v94
	v_exp_f32_e32 v99, v99
	s_nop 0
	v_add_f32_e32 v99, 1.0, v99
	v_rcp_f32_e32 v100, v99
	v_mul_f32_e32 v99, 0xbfb8aa3b, v95
	v_exp_f32_e32 v99, v99
	s_nop 0
	v_add_f32_e32 v99, 1.0, v99
	v_rcp_f32_e32 v101, v99
	v_pk_mul_f32 v[90:91], v[90:91], v[98:99] op_sel_hi:[1,0]
	v_pk_mul_f32 v[92:93], v[92:93], v[98:99] op_sel_hi:[1,0]
	v_pk_mul_f32 v[86:87], v[86:87], v[98:99] op_sel_hi:[1,0]
	v_pk_mul_f32 v[94:95], v[94:95], v[100:101]
	v_pk_mul_f32 v[82:83], v[82:83], v[98:99] op_sel_hi:[1,0]
	v_pk_mul_f32 v[90:91], v[90:91], v[94:95]
	v_pk_mul_f32 v[94:95], v[96:97], v[98:99] op_sel_hi:[1,0]
	v_cvt_pk_bf16_f32 v90, v90, v91
	v_mul_f32_e32 v96, 0xbfb8aa3b, v94
	v_mul_f32_e32 v97, 0xbfb8aa3b, v95
	v_exp_f32_e32 v96, v96
	v_exp_f32_e32 v97, v97
	v_pk_mul_f32 v[84:85], v[84:85], v[98:99] op_sel_hi:[1,0]
	v_add_f32_e32 v96, 1.0, v96
	v_add_f32_e32 v97, 1.0, v97
	v_rcp_f32_e32 v96, v96
	v_rcp_f32_e32 v97, v97
	s_nop 0
	v_pk_mul_f32 v[94:95], v[94:95], v[96:97]
	s_nop 0
	v_pk_mul_f32 v[92:93], v[92:93], v[94:95]
	s_nop 0
	v_cvt_pk_bf16_f32 v91, v92, v93
	v_mad_i64_i32 v[92:93], s[20:21], v106, s1, v[122:123]
	v_lshl_add_u64 v[92:93], v[92:93], 0, v[124:125]
	v_lshl_add_u64 v[244:245], v[92:93], 0, v[246:247]
	v_mov_b32_e32 v236, v90
	v_mov_b32_e32 v237, v91
	v_mul_f32_e32 v90, 0xbfb8aa3b, v86
	v_mul_f32_e32 v91, 0xbfb8aa3b, v87
	v_exp_f32_e32 v90, v90
	v_exp_f32_e32 v91, v91
	v_add_f32_e32 v90, 1.0, v90
	v_add_f32_e32 v91, 1.0, v91
	v_rcp_f32_e32 v90, v90
	v_rcp_f32_e32 v91, v91
	s_nop 0
	v_pk_mul_f32 v[86:87], v[86:87], v[90:91]
	s_nop 0
	v_pk_mul_f32 v[82:83], v[82:83], v[86:87]
	v_pk_mul_f32 v[86:87], v[88:89], v[98:99] op_sel_hi:[1,0]
	v_or_b32_e32 v90, 48, v140
	v_mul_f32_e32 v88, 0xbfb8aa3b, v86
	v_mul_f32_e32 v89, 0xbfb8aa3b, v87
	v_exp_f32_e32 v88, v88
	v_exp_f32_e32 v89, v89
	v_cvt_pk_bf16_f32 v82, v82, v83
	v_ashrrev_i32_e32 v91, 31, v90
	v_add_f32_e32 v88, 1.0, v88
	v_add_f32_e32 v89, 1.0, v89
	v_rcp_f32_e32 v88, v88
	v_rcp_f32_e32 v89, v89
	s_nop 0
	v_pk_mul_f32 v[86:87], v[86:87], v[88:89]
	s_nop 0
	v_pk_mul_f32 v[84:85], v[84:85], v[86:87]
	s_nop 0
	v_cvt_pk_bf16_f32 v83, v84, v85
	v_mov_b32_e32 v240, v82
	v_mov_b32_e32 v241, v83
	v_add_f32_e32 v216, v216, v217
	v_add_f32_e32 v218, v218, v219
	v_add_f32_e32 v216, v216, v218
	v_mov_b32_e32 v217, v216
	s_nop 1
	v_permlane16_swap_b32_e32 v216, v217
	v_add_f32_e32 v216, v216, v217
	v_mov_b32_e32 v217, v216
	s_nop 1
	v_permlane32_swap_b32_e32 v216, v217
	v_add_f32_e32 v82, v216, v217
	v_fmamk_f32 v82, v82, 0x3a800000, v161
	v_cmp_gt_f32_e32 vcc, s62, v82
	v_mul_f32_e32 v83, 0x4b800000, v82
	s_nop 0
	v_cndmask_b32_e32 v82, v82, v83, vcc
	v_rsq_f32_e32 v82, v82
	s_nop 0
	v_mul_f32_e32 v83, 0x45800000, v82
	v_cndmask_b32_e32 v82, v82, v83, vcc
	v_pk_mul_f32 v[78:79], v[78:79], v[82:83] op_sel_hi:[1,0]
	s_nop 0
	v_mul_f32_e32 v83, 0xbfb8aa3b, v78
	v_exp_f32_e32 v83, v83
	s_nop 0
	v_add_f32_e32 v83, 1.0, v83
	v_rcp_f32_e32 v84, v83
	v_mul_f32_e32 v83, 0xbfb8aa3b, v79
	v_exp_f32_e32 v83, v83
	s_nop 0
	v_add_f32_e32 v83, 1.0, v83
	v_rcp_f32_e32 v85, v83
	v_pk_mul_f32 v[74:75], v[74:75], v[82:83] op_sel_hi:[1,0]
	v_pk_mul_f32 v[76:77], v[76:77], v[82:83] op_sel_hi:[1,0]
	v_pk_mul_f32 v[70:71], v[70:71], v[82:83] op_sel_hi:[1,0]
	v_pk_mul_f32 v[78:79], v[78:79], v[84:85]
	v_pk_mul_f32 v[66:67], v[66:67], v[82:83] op_sel_hi:[1,0]
	v_pk_mul_f32 v[74:75], v[74:75], v[78:79]
	v_pk_mul_f32 v[78:79], v[80:81], v[82:83] op_sel_hi:[1,0]
	v_cvt_pk_bf16_f32 v74, v74, v75
	v_mul_f32_e32 v80, 0xbfb8aa3b, v78
	v_mul_f32_e32 v81, 0xbfb8aa3b, v79
	v_exp_f32_e32 v80, v80
	v_exp_f32_e32 v81, v81
	v_pk_mul_f32 v[68:69], v[68:69], v[82:83] op_sel_hi:[1,0]
	v_add_f32_e32 v80, 1.0, v80
	v_add_f32_e32 v81, 1.0, v81
	v_rcp_f32_e32 v80, v80
	v_rcp_f32_e32 v81, v81
	s_nop 0
	v_pk_mul_f32 v[78:79], v[78:79], v[80:81]
	s_nop 0
	v_pk_mul_f32 v[76:77], v[76:77], v[78:79]
	s_nop 0
	v_cvt_pk_bf16_f32 v75, v76, v77
	v_mad_i64_i32 v[76:77], s[20:21], v90, s1, v[122:123]
	v_lshl_add_u64 v[76:77], v[76:77], 0, v[124:125]
	v_mov_b32_e32 v238, v74
	v_mov_b32_e32 v239, v75
	s_nop 1
	v_permlane16_swap_b32_e32 v236, v238
	v_permlane16_swap_b32_e32 v237, v239
	global_store_dwordx4 v[244:245], v[236:239], off
	v_mul_f32_e32 v74, 0xbfb8aa3b, v70
	v_mul_f32_e32 v75, 0xbfb8aa3b, v71
	v_exp_f32_e32 v74, v74
	v_exp_f32_e32 v75, v75
	v_add_f32_e32 v74, 1.0, v74
	v_add_f32_e32 v75, 1.0, v75
	v_rcp_f32_e32 v74, v74
	v_rcp_f32_e32 v75, v75
	s_nop 0
	v_pk_mul_f32 v[70:71], v[70:71], v[74:75]
	s_nop 0
	v_pk_mul_f32 v[66:67], v[66:67], v[70:71]
	v_pk_mul_f32 v[70:71], v[72:73], v[82:83] op_sel_hi:[1,0]
	v_add_u32_e32 v74, 0x80, v140
	v_mul_f32_e32 v72, 0xbfb8aa3b, v70
	v_mul_f32_e32 v73, 0xbfb8aa3b, v71
	v_exp_f32_e32 v72, v72
	v_exp_f32_e32 v73, v73
	v_cvt_pk_bf16_f32 v66, v66, v67
	v_ashrrev_i32_e32 v75, 31, v74
	v_add_f32_e32 v72, 1.0, v72
	v_add_f32_e32 v73, 1.0, v73
	v_rcp_f32_e32 v72, v72
	v_rcp_f32_e32 v73, v73
	s_nop 0
	v_pk_mul_f32 v[70:71], v[70:71], v[72:73]
	s_nop 0
	v_pk_mul_f32 v[68:69], v[68:69], v[70:71]
	s_nop 0
	v_cvt_pk_bf16_f32 v67, v68, v69
	v_mov_b32_e32 v242, v66
	v_mov_b32_e32 v243, v67
	s_nop 1
	v_permlane16_swap_b32_e32 v240, v242
	v_permlane16_swap_b32_e32 v241, v243
	global_store_dwordx4 v[244:245], v[240:243], off offset:128
	v_add_f32_e32 v220, v220, v221
	v_add_f32_e32 v222, v222, v223
	v_add_f32_e32 v220, v220, v222
	v_mov_b32_e32 v221, v220
	s_nop 1
	v_permlane16_swap_b32_e32 v220, v221
	v_add_f32_e32 v220, v220, v221
	v_mov_b32_e32 v221, v220
	s_nop 1
	v_permlane32_swap_b32_e32 v220, v221
	v_add_f32_e32 v66, v220, v221
	v_fmamk_f32 v66, v66, 0x3a800000, v161
	v_cmp_gt_f32_e32 vcc, s62, v66
	v_mul_f32_e32 v67, 0x4b800000, v66
	s_nop 0
	v_cndmask_b32_e32 v66, v66, v67, vcc
	v_rsq_f32_e32 v66, v66
	s_nop 0
	v_mul_f32_e32 v67, 0x45800000, v66
	v_cndmask_b32_e32 v66, v66, v67, vcc
	v_pk_mul_f32 v[62:63], v[62:63], v[66:67] op_sel_hi:[1,0]
	s_nop 0
	v_mul_f32_e32 v67, 0xbfb8aa3b, v62
	v_exp_f32_e32 v67, v67
	s_nop 0
	v_add_f32_e32 v67, 1.0, v67
	v_rcp_f32_e32 v68, v67
	v_mul_f32_e32 v67, 0xbfb8aa3b, v63
	v_exp_f32_e32 v67, v67
	s_nop 0
	v_add_f32_e32 v67, 1.0, v67
	v_rcp_f32_e32 v69, v67
	v_pk_mul_f32 v[58:59], v[58:59], v[66:67] op_sel_hi:[1,0]
	v_pk_mul_f32 v[60:61], v[60:61], v[66:67] op_sel_hi:[1,0]
	v_pk_mul_f32 v[54:55], v[54:55], v[66:67] op_sel_hi:[1,0]
	v_pk_mul_f32 v[62:63], v[62:63], v[68:69]
	v_pk_mul_f32 v[50:51], v[50:51], v[66:67] op_sel_hi:[1,0]
	v_pk_mul_f32 v[58:59], v[58:59], v[62:63]
	v_pk_mul_f32 v[62:63], v[64:65], v[66:67] op_sel_hi:[1,0]
	v_cvt_pk_bf16_f32 v58, v58, v59
	v_mul_f32_e32 v64, 0xbfb8aa3b, v62
	v_mul_f32_e32 v65, 0xbfb8aa3b, v63
	v_exp_f32_e32 v64, v64
	v_exp_f32_e32 v65, v65
	v_pk_mul_f32 v[52:53], v[52:53], v[66:67] op_sel_hi:[1,0]
	v_add_f32_e32 v64, 1.0, v64
	v_add_f32_e32 v65, 1.0, v65
	v_rcp_f32_e32 v64, v64
	v_rcp_f32_e32 v65, v65
	s_nop 0
	v_pk_mul_f32 v[62:63], v[62:63], v[64:65]
	s_nop 0
	v_pk_mul_f32 v[60:61], v[60:61], v[62:63]
	s_nop 0
	v_cvt_pk_bf16_f32 v59, v60, v61
	v_mad_i64_i32 v[60:61], s[20:21], v74, s1, v[122:123]
	v_lshl_add_u64 v[60:61], v[60:61], 0, v[124:125]
	v_lshl_add_u64 v[244:245], v[60:61], 0, v[246:247]
	v_mov_b32_e32 v236, v58
	v_mov_b32_e32 v237, v59
	v_mul_f32_e32 v58, 0xbfb8aa3b, v54
	v_mul_f32_e32 v59, 0xbfb8aa3b, v55
	v_exp_f32_e32 v58, v58
	v_exp_f32_e32 v59, v59
	v_add_f32_e32 v58, 1.0, v58
	v_add_f32_e32 v59, 1.0, v59
	v_rcp_f32_e32 v58, v58
	v_rcp_f32_e32 v59, v59
	s_nop 0
	v_pk_mul_f32 v[54:55], v[54:55], v[58:59]
	s_nop 0
	v_pk_mul_f32 v[50:51], v[50:51], v[54:55]
	v_pk_mul_f32 v[54:55], v[56:57], v[66:67] op_sel_hi:[1,0]
	v_add_u32_e32 v58, 0x90, v140
	v_mul_f32_e32 v56, 0xbfb8aa3b, v54
	v_mul_f32_e32 v57, 0xbfb8aa3b, v55
	v_exp_f32_e32 v56, v56
	v_exp_f32_e32 v57, v57
	v_cvt_pk_bf16_f32 v50, v50, v51
	v_ashrrev_i32_e32 v59, 31, v58
	v_add_f32_e32 v56, 1.0, v56
	v_add_f32_e32 v57, 1.0, v57
	v_rcp_f32_e32 v56, v56
	v_rcp_f32_e32 v57, v57
	s_nop 0
	v_pk_mul_f32 v[54:55], v[54:55], v[56:57]
	s_nop 0
	v_pk_mul_f32 v[52:53], v[52:53], v[54:55]
	s_nop 0
	v_cvt_pk_bf16_f32 v51, v52, v53
	v_mov_b32_e32 v240, v50
	v_mov_b32_e32 v241, v51
	v_add_f32_e32 v224, v224, v225
	v_add_f32_e32 v226, v226, v227
	v_add_f32_e32 v224, v224, v226
	v_mov_b32_e32 v225, v224
	s_nop 1
	v_permlane16_swap_b32_e32 v224, v225
	v_add_f32_e32 v224, v224, v225
	v_mov_b32_e32 v225, v224
	s_nop 1
	v_permlane32_swap_b32_e32 v224, v225
	v_add_f32_e32 v50, v224, v225
	v_fmamk_f32 v50, v50, 0x3a800000, v161
	v_cmp_gt_f32_e32 vcc, s62, v50
	v_mul_f32_e32 v51, 0x4b800000, v50
	s_nop 0
	v_cndmask_b32_e32 v50, v50, v51, vcc
	v_rsq_f32_e32 v50, v50
	s_nop 0
	v_mul_f32_e32 v51, 0x45800000, v50
	v_cndmask_b32_e32 v50, v50, v51, vcc
	v_pk_mul_f32 v[46:47], v[46:47], v[50:51] op_sel_hi:[1,0]
	s_nop 0
	v_mul_f32_e32 v51, 0xbfb8aa3b, v46
	v_exp_f32_e32 v51, v51
	s_nop 0
	v_add_f32_e32 v51, 1.0, v51
	v_rcp_f32_e32 v52, v51
	v_mul_f32_e32 v51, 0xbfb8aa3b, v47
	v_exp_f32_e32 v51, v51
	s_nop 0
	v_add_f32_e32 v51, 1.0, v51
	v_rcp_f32_e32 v53, v51
	v_pk_mul_f32 v[42:43], v[42:43], v[50:51] op_sel_hi:[1,0]
	v_pk_mul_f32 v[44:45], v[44:45], v[50:51] op_sel_hi:[1,0]
	v_pk_mul_f32 v[38:39], v[38:39], v[50:51] op_sel_hi:[1,0]
	v_pk_mul_f32 v[46:47], v[46:47], v[52:53]
	v_pk_mul_f32 v[34:35], v[34:35], v[50:51] op_sel_hi:[1,0]
	v_pk_mul_f32 v[42:43], v[42:43], v[46:47]
	v_pk_mul_f32 v[46:47], v[48:49], v[50:51] op_sel_hi:[1,0]
	v_cvt_pk_bf16_f32 v42, v42, v43
	v_mul_f32_e32 v48, 0xbfb8aa3b, v46
	v_mul_f32_e32 v49, 0xbfb8aa3b, v47
	v_exp_f32_e32 v48, v48
	v_exp_f32_e32 v49, v49
	v_pk_mul_f32 v[36:37], v[36:37], v[50:51] op_sel_hi:[1,0]
	v_add_f32_e32 v48, 1.0, v48
	v_add_f32_e32 v49, 1.0, v49
	v_rcp_f32_e32 v48, v48
	v_rcp_f32_e32 v49, v49
	s_nop 0
	v_pk_mul_f32 v[46:47], v[46:47], v[48:49]
	s_nop 0
	v_pk_mul_f32 v[44:45], v[44:45], v[46:47]
	s_nop 0
	v_cvt_pk_bf16_f32 v43, v44, v45
	v_mad_i64_i32 v[44:45], s[20:21], v58, s1, v[122:123]
	v_lshl_add_u64 v[44:45], v[44:45], 0, v[124:125]
	v_mov_b32_e32 v238, v42
	v_mov_b32_e32 v239, v43
	s_nop 1
	v_permlane16_swap_b32_e32 v236, v238
	v_permlane16_swap_b32_e32 v237, v239
	global_store_dwordx4 v[244:245], v[236:239], off
	v_mul_f32_e32 v42, 0xbfb8aa3b, v38
	v_mul_f32_e32 v43, 0xbfb8aa3b, v39
	v_exp_f32_e32 v42, v42
	v_exp_f32_e32 v43, v43
	v_add_f32_e32 v42, 1.0, v42
	v_add_f32_e32 v43, 1.0, v43
	v_rcp_f32_e32 v42, v42
	v_rcp_f32_e32 v43, v43
	s_nop 0
	v_pk_mul_f32 v[38:39], v[38:39], v[42:43]
	s_nop 0
	v_pk_mul_f32 v[34:35], v[34:35], v[38:39]
	v_pk_mul_f32 v[38:39], v[40:41], v[50:51] op_sel_hi:[1,0]
	v_add_u32_e32 v42, 0xa0, v140
	v_mul_f32_e32 v40, 0xbfb8aa3b, v38
	v_mul_f32_e32 v41, 0xbfb8aa3b, v39
	v_exp_f32_e32 v40, v40
	v_exp_f32_e32 v41, v41
	v_cvt_pk_bf16_f32 v34, v34, v35
	v_ashrrev_i32_e32 v43, 31, v42
	v_add_f32_e32 v40, 1.0, v40
	v_add_f32_e32 v41, 1.0, v41
	v_rcp_f32_e32 v40, v40
	v_rcp_f32_e32 v41, v41
	s_nop 0
	v_pk_mul_f32 v[38:39], v[38:39], v[40:41]
	s_nop 0
	v_pk_mul_f32 v[36:37], v[36:37], v[38:39]
	s_nop 0
	v_cvt_pk_bf16_f32 v35, v36, v37
	v_mov_b32_e32 v242, v34
	v_mov_b32_e32 v243, v35
	s_nop 1
	v_permlane16_swap_b32_e32 v240, v242
	v_permlane16_swap_b32_e32 v241, v243
	global_store_dwordx4 v[244:245], v[240:243], off offset:128
	v_add_f32_e32 v228, v228, v229
	v_add_f32_e32 v230, v230, v231
	v_add_f32_e32 v228, v228, v230
	v_mov_b32_e32 v229, v228
	s_nop 1
	v_permlane16_swap_b32_e32 v228, v229
	v_add_f32_e32 v228, v228, v229
	v_mov_b32_e32 v229, v228
	s_nop 1
	v_permlane32_swap_b32_e32 v228, v229
	v_add_f32_e32 v34, v228, v229
	v_fmamk_f32 v34, v34, 0x3a800000, v161
	v_cmp_gt_f32_e32 vcc, s62, v34
	v_mul_f32_e32 v35, 0x4b800000, v34
	s_nop 0
	v_cndmask_b32_e32 v34, v34, v35, vcc
	v_rsq_f32_e32 v34, v34
	s_nop 0
	v_mul_f32_e32 v35, 0x45800000, v34
	v_cndmask_b32_e32 v34, v34, v35, vcc
	v_pk_mul_f32 v[30:31], v[30:31], v[34:35] op_sel_hi:[1,0]
	s_nop 0
	v_mul_f32_e32 v35, 0xbfb8aa3b, v30
	v_exp_f32_e32 v35, v35
	s_nop 0
	v_add_f32_e32 v35, 1.0, v35
	v_rcp_f32_e32 v36, v35
	v_mul_f32_e32 v35, 0xbfb8aa3b, v31
	v_exp_f32_e32 v35, v35
	s_nop 0
	v_add_f32_e32 v35, 1.0, v35
	v_rcp_f32_e32 v37, v35
	v_pk_mul_f32 v[26:27], v[26:27], v[34:35] op_sel_hi:[1,0]
	v_pk_mul_f32 v[28:29], v[28:29], v[34:35] op_sel_hi:[1,0]
	v_pk_mul_f32 v[22:23], v[22:23], v[34:35] op_sel_hi:[1,0]
	v_pk_mul_f32 v[30:31], v[30:31], v[36:37]
	v_pk_mul_f32 v[18:19], v[18:19], v[34:35] op_sel_hi:[1,0]
	v_pk_mul_f32 v[26:27], v[26:27], v[30:31]
	v_pk_mul_f32 v[30:31], v[32:33], v[34:35] op_sel_hi:[1,0]
	v_cvt_pk_bf16_f32 v26, v26, v27
	v_mul_f32_e32 v32, 0xbfb8aa3b, v30
	v_mul_f32_e32 v33, 0xbfb8aa3b, v31
	v_exp_f32_e32 v32, v32
	v_exp_f32_e32 v33, v33
	v_pk_mul_f32 v[20:21], v[20:21], v[34:35] op_sel_hi:[1,0]
	v_add_f32_e32 v32, 1.0, v32
	v_add_f32_e32 v33, 1.0, v33
	v_rcp_f32_e32 v32, v32
	v_rcp_f32_e32 v33, v33
	s_nop 0
	v_pk_mul_f32 v[30:31], v[30:31], v[32:33]
	s_nop 0
	v_pk_mul_f32 v[28:29], v[28:29], v[30:31]
	s_nop 0
	v_cvt_pk_bf16_f32 v27, v28, v29
	v_mad_i64_i32 v[28:29], s[20:21], v42, s1, v[122:123]
	v_lshl_add_u64 v[28:29], v[28:29], 0, v[124:125]
	v_lshl_add_u64 v[244:245], v[28:29], 0, v[246:247]
	v_mov_b32_e32 v236, v26
	v_mov_b32_e32 v237, v27
	v_mul_f32_e32 v26, 0xbfb8aa3b, v22
	v_mul_f32_e32 v27, 0xbfb8aa3b, v23
	v_exp_f32_e32 v26, v26
	v_exp_f32_e32 v27, v27
	v_add_f32_e32 v26, 1.0, v26
	v_add_f32_e32 v27, 1.0, v27
	v_rcp_f32_e32 v26, v26
	v_rcp_f32_e32 v27, v27
	s_nop 0
	v_pk_mul_f32 v[22:23], v[22:23], v[26:27]
	s_nop 0
	v_pk_mul_f32 v[18:19], v[18:19], v[22:23]
	v_pk_mul_f32 v[22:23], v[24:25], v[34:35] op_sel_hi:[1,0]
	v_add_u32_e32 v26, 0xb0, v140
	v_mul_f32_e32 v24, 0xbfb8aa3b, v22
	v_mul_f32_e32 v25, 0xbfb8aa3b, v23
	v_exp_f32_e32 v24, v24
	v_exp_f32_e32 v25, v25
	v_cvt_pk_bf16_f32 v18, v18, v19
	v_ashrrev_i32_e32 v27, 31, v26
	v_add_f32_e32 v24, 1.0, v24
	v_add_f32_e32 v25, 1.0, v25
	v_rcp_f32_e32 v24, v24
	v_rcp_f32_e32 v25, v25
	s_nop 0
	v_pk_mul_f32 v[22:23], v[22:23], v[24:25]
	s_nop 0
	v_pk_mul_f32 v[20:21], v[20:21], v[22:23]
	s_nop 0
	v_cvt_pk_bf16_f32 v19, v20, v21
	v_mov_b32_e32 v240, v18
	v_mov_b32_e32 v241, v19
	v_add_f32_e32 v232, v232, v233
	v_add_f32_e32 v234, v234, v235
	v_add_f32_e32 v232, v232, v234
	v_mov_b32_e32 v233, v232
	s_nop 1
	v_permlane16_swap_b32_e32 v232, v233
	v_add_f32_e32 v232, v232, v233
	v_mov_b32_e32 v233, v232
	s_nop 1
	v_permlane32_swap_b32_e32 v232, v233
	v_add_f32_e32 v18, v232, v233
	v_fmamk_f32 v18, v18, 0x3a800000, v161
	v_cmp_gt_f32_e32 vcc, s62, v18
	v_mul_f32_e32 v19, 0x4b800000, v18
	s_nop 0
	v_cndmask_b32_e32 v18, v18, v19, vcc
	v_rsq_f32_e32 v18, v18
	s_nop 0
	v_mul_f32_e32 v19, 0x45800000, v18
	v_cndmask_b32_e32 v18, v18, v19, vcc
	v_pk_mul_f32 v[14:15], v[14:15], v[18:19] op_sel_hi:[1,0]
	s_andn2_b64 vcc, exec, s[6:7]
	v_mul_f32_e32 v19, 0xbfb8aa3b, v14
	v_exp_f32_e32 v19, v19
	s_nop 0
	v_add_f32_e32 v19, 1.0, v19
	v_rcp_f32_e32 v20, v19
	v_mul_f32_e32 v19, 0xbfb8aa3b, v15
	v_exp_f32_e32 v19, v19
	s_nop 0
	v_add_f32_e32 v19, 1.0, v19
	v_rcp_f32_e32 v21, v19
	v_pk_mul_f32 v[10:11], v[10:11], v[18:19] op_sel_hi:[1,0]
	v_pk_mul_f32 v[12:13], v[12:13], v[18:19] op_sel_hi:[1,0]
	v_pk_mul_f32 v[6:7], v[6:7], v[18:19] op_sel_hi:[1,0]
	v_pk_mul_f32 v[14:15], v[14:15], v[20:21]
	v_pk_mul_f32 v[2:3], v[2:3], v[18:19] op_sel_hi:[1,0]
	v_pk_mul_f32 v[10:11], v[10:11], v[14:15]
	v_pk_mul_f32 v[14:15], v[16:17], v[18:19] op_sel_hi:[1,0]
	v_cvt_pk_bf16_f32 v10, v10, v11
	v_mul_f32_e32 v16, 0xbfb8aa3b, v14
	v_mul_f32_e32 v17, 0xbfb8aa3b, v15
	v_exp_f32_e32 v16, v16
	v_exp_f32_e32 v17, v17
	v_pk_mul_f32 v[4:5], v[4:5], v[18:19] op_sel_hi:[1,0]
	v_add_f32_e32 v16, 1.0, v16
	v_add_f32_e32 v17, 1.0, v17
	v_rcp_f32_e32 v16, v16
	v_rcp_f32_e32 v17, v17
	s_nop 0
	v_pk_mul_f32 v[14:15], v[14:15], v[16:17]
	s_nop 0
	v_pk_mul_f32 v[12:13], v[12:13], v[14:15]
	s_nop 0
	v_cvt_pk_bf16_f32 v11, v12, v13
	v_mad_i64_i32 v[12:13], s[20:21], v26, s1, v[122:123]
	v_lshl_add_u64 v[12:13], v[12:13], 0, v[124:125]
	v_mov_b32_e32 v238, v10
	v_mov_b32_e32 v239, v11
	s_nop 1
	v_permlane16_swap_b32_e32 v236, v238
	v_permlane16_swap_b32_e32 v237, v239
	global_store_dwordx4 v[244:245], v[236:239], off
	v_mul_f32_e32 v10, 0xbfb8aa3b, v6
	v_mul_f32_e32 v11, 0xbfb8aa3b, v7
	v_exp_f32_e32 v10, v10
	v_exp_f32_e32 v11, v11
	s_mov_b64 s[20:21], -1
	v_add_f32_e32 v10, 1.0, v10
	v_add_f32_e32 v11, 1.0, v11
	v_rcp_f32_e32 v10, v10
	v_rcp_f32_e32 v11, v11
	s_nop 0
	v_pk_mul_f32 v[6:7], v[6:7], v[10:11]
	s_nop 0
	v_pk_mul_f32 v[2:3], v[2:3], v[6:7]
	v_pk_mul_f32 v[6:7], v[8:9], v[18:19] op_sel_hi:[1,0]
	v_cvt_pk_bf16_f32 v2, v2, v3
	v_mul_f32_e32 v8, 0xbfb8aa3b, v6
	v_mul_f32_e32 v9, 0xbfb8aa3b, v7
	v_exp_f32_e32 v8, v8
	v_exp_f32_e32 v9, v9
	v_add_f32_e32 v8, 1.0, v8
	v_add_f32_e32 v9, 1.0, v9
	v_rcp_f32_e32 v8, v8
	v_rcp_f32_e32 v9, v9
	s_nop 0
	v_pk_mul_f32 v[6:7], v[6:7], v[8:9]
	s_nop 0
	v_pk_mul_f32 v[4:5], v[4:5], v[6:7]
	s_nop 0
	v_cvt_pk_bf16_f32 v3, v4, v5
	v_mov_b32_e32 v242, v2
	v_mov_b32_e32 v243, v3
	s_nop 1
	v_permlane16_swap_b32_e32 v240, v242
	v_permlane16_swap_b32_e32 v241, v243
	global_store_dwordx4 v[244:245], v[240:243], off offset:128
	s_cbranch_vccnz .LBB0_1598
	s_andn2_b64 vcc, exec, s[4:5]
	s_cbranch_vccnz .LBB0_1597
	s_barrier
	s_branch .LBB0_1597
